# v063 + modulation GEMV with deep load prefetch (fill: 18 loads together; k loop: 3 steps in flight) + P0 rebalance R=3
# baseline (speedup 1.0000x reference)
.LBB0_10:
	s_mov_b64 s[14:15], 0
	v_mov_b64_e32 v[2:3], v[50:51]
	v_mov_b32_e32 v4, v81
	v_mov_b32_e32 v5, v1
	global_load_dword v8, v[2:3], off
	v_lshl_add_u64 v[2:3], v[2:3], 0, s[6:7]
	global_load_dword v9, v[2:3], off
	v_lshl_add_u64 v[2:3], v[2:3], 0, s[6:7]
	global_load_dword v10, v[2:3], off
	v_lshl_add_u64 v[2:3], v[2:3], 0, s[6:7]
	global_load_dword v11, v[2:3], off
	v_lshl_add_u64 v[2:3], v[2:3], 0, s[6:7]
	global_load_dword v12, v[2:3], off
	v_lshl_add_u64 v[2:3], v[2:3], 0, s[6:7]
	global_load_dword v13, v[2:3], off
	v_lshl_add_u64 v[2:3], v[2:3], 0, s[6:7]
	global_load_dword v14, v[2:3], off
	v_lshl_add_u64 v[2:3], v[2:3], 0, s[6:7]
	global_load_dword v15, v[2:3], off
	v_lshl_add_u64 v[2:3], v[2:3], 0, s[6:7]
	global_load_dword v16, v[2:3], off
	v_lshl_add_u64 v[2:3], v[2:3], 0, s[6:7]
	global_load_dword v17, v[2:3], off
	v_lshl_add_u64 v[2:3], v[2:3], 0, s[6:7]
	global_load_dword v18, v[2:3], off
	v_lshl_add_u64 v[2:3], v[2:3], 0, s[6:7]
	global_load_dword v19, v[2:3], off
	v_lshl_add_u64 v[2:3], v[2:3], 0, s[6:7]
	global_load_dword v20, v[2:3], off
	v_lshl_add_u64 v[2:3], v[2:3], 0, s[6:7]
	global_load_dword v21, v[2:3], off
	v_lshl_add_u64 v[2:3], v[2:3], 0, s[6:7]
	global_load_dword v22, v[2:3], off
	v_lshl_add_u64 v[2:3], v[2:3], 0, s[6:7]
	global_load_dword v23, v[2:3], off
	v_lshl_add_u64 v[2:3], v[2:3], 0, s[6:7]
	v_lshlrev_b32_e32 v46, 2, v1
	v_lshl_add_u64 v[6:7], s[4:5], 0, v[46:47]
	global_load_dword v24, v[6:7], off
	global_load_dword v25, v[6:7], off offset:2048
	s_waitcnt vmcnt(17)
	v_mul_f32_e32 v26, 0xbfb8aa3b, v8
	v_exp_f32_e32 v26, v26
	s_nop 0
	v_add_f32_e32 v26, 1.0, v26
	v_rcp_f32_e32 v26, v26
	s_nop 0
	v_mul_f32_e32 v8, v8, v26
	ds_write_b32 v81, v8 offset:0
	s_waitcnt vmcnt(16)
	v_mul_f32_e32 v27, 0xbfb8aa3b, v9
	v_exp_f32_e32 v27, v27
	s_nop 0
	v_add_f32_e32 v27, 1.0, v27
	v_rcp_f32_e32 v27, v27
	s_nop 0
	v_mul_f32_e32 v9, v9, v27
	ds_write_b32 v81, v9 offset:2048
	s_waitcnt vmcnt(15)
	v_mul_f32_e32 v26, 0xbfb8aa3b, v10
	v_exp_f32_e32 v26, v26
	s_nop 0
	v_add_f32_e32 v26, 1.0, v26
	v_rcp_f32_e32 v26, v26
	s_nop 0
	v_mul_f32_e32 v10, v10, v26
	ds_write_b32 v81, v10 offset:4096
	s_waitcnt vmcnt(14)
	v_mul_f32_e32 v27, 0xbfb8aa3b, v11
	v_exp_f32_e32 v27, v27
	s_nop 0
	v_add_f32_e32 v27, 1.0, v27
	v_rcp_f32_e32 v27, v27
	s_nop 0
	v_mul_f32_e32 v11, v11, v27
	ds_write_b32 v81, v11 offset:6144
	s_waitcnt vmcnt(13)
	v_mul_f32_e32 v26, 0xbfb8aa3b, v12
	v_exp_f32_e32 v26, v26
	s_nop 0
	v_add_f32_e32 v26, 1.0, v26
	v_rcp_f32_e32 v26, v26
	s_nop 0
	v_mul_f32_e32 v12, v12, v26
	ds_write_b32 v81, v12 offset:8192
	s_waitcnt vmcnt(12)
	v_mul_f32_e32 v27, 0xbfb8aa3b, v13
	v_exp_f32_e32 v27, v27
	s_nop 0
	v_add_f32_e32 v27, 1.0, v27
	v_rcp_f32_e32 v27, v27
	s_nop 0
	v_mul_f32_e32 v13, v13, v27
	ds_write_b32 v81, v13 offset:10240
	s_waitcnt vmcnt(11)
	v_mul_f32_e32 v26, 0xbfb8aa3b, v14
	v_exp_f32_e32 v26, v26
	s_nop 0
	v_add_f32_e32 v26, 1.0, v26
	v_rcp_f32_e32 v26, v26
	s_nop 0
	v_mul_f32_e32 v14, v14, v26
	ds_write_b32 v81, v14 offset:12288
	s_waitcnt vmcnt(10)
	v_mul_f32_e32 v27, 0xbfb8aa3b, v15
	v_exp_f32_e32 v27, v27
	s_nop 0
	v_add_f32_e32 v27, 1.0, v27
	v_rcp_f32_e32 v27, v27
	s_nop 0
	v_mul_f32_e32 v15, v15, v27
	ds_write_b32 v81, v15 offset:14336
	s_waitcnt vmcnt(9)
	v_mul_f32_e32 v26, 0xbfb8aa3b, v16
	v_exp_f32_e32 v26, v26
	s_nop 0
	v_add_f32_e32 v26, 1.0, v26
	v_rcp_f32_e32 v26, v26
	s_nop 0
	v_mul_f32_e32 v16, v16, v26
	ds_write_b32 v81, v16 offset:16384
	s_waitcnt vmcnt(8)
	v_mul_f32_e32 v27, 0xbfb8aa3b, v17
	v_exp_f32_e32 v27, v27
	s_nop 0
	v_add_f32_e32 v27, 1.0, v27
	v_rcp_f32_e32 v27, v27
	s_nop 0
	v_mul_f32_e32 v17, v17, v27
	ds_write_b32 v81, v17 offset:18432
	s_waitcnt vmcnt(7)
	v_mul_f32_e32 v26, 0xbfb8aa3b, v18
	v_exp_f32_e32 v26, v26
	s_nop 0
	v_add_f32_e32 v26, 1.0, v26
	v_rcp_f32_e32 v26, v26
	s_nop 0
	v_mul_f32_e32 v18, v18, v26
	ds_write_b32 v81, v18 offset:20480
	s_waitcnt vmcnt(6)
	v_mul_f32_e32 v27, 0xbfb8aa3b, v19
	v_exp_f32_e32 v27, v27
	s_nop 0
	v_add_f32_e32 v27, 1.0, v27
	v_rcp_f32_e32 v27, v27
	s_nop 0
	v_mul_f32_e32 v19, v19, v27
	ds_write_b32 v81, v19 offset:22528
	s_waitcnt vmcnt(5)
	v_mul_f32_e32 v26, 0xbfb8aa3b, v20
	v_exp_f32_e32 v26, v26
	s_nop 0
	v_add_f32_e32 v26, 1.0, v26
	v_rcp_f32_e32 v26, v26
	s_nop 0
	v_mul_f32_e32 v20, v20, v26
	ds_write_b32 v81, v20 offset:24576
	s_waitcnt vmcnt(4)
	v_mul_f32_e32 v27, 0xbfb8aa3b, v21
	v_exp_f32_e32 v27, v27
	s_nop 0
	v_add_f32_e32 v27, 1.0, v27
	v_rcp_f32_e32 v27, v27
	s_nop 0
	v_mul_f32_e32 v21, v21, v27
	ds_write_b32 v81, v21 offset:26624
	s_waitcnt vmcnt(3)
	v_mul_f32_e32 v26, 0xbfb8aa3b, v22
	v_exp_f32_e32 v26, v26
	s_nop 0
	v_add_f32_e32 v26, 1.0, v26
	v_rcp_f32_e32 v26, v26
	s_nop 0
	v_mul_f32_e32 v22, v22, v26
	ds_write_b32 v81, v22 offset:28672
	s_waitcnt vmcnt(2)
	v_mul_f32_e32 v27, 0xbfb8aa3b, v23
	v_exp_f32_e32 v27, v27
	s_nop 0
	v_add_f32_e32 v27, 1.0, v27
	v_rcp_f32_e32 v27, v27
	s_nop 0
	v_mul_f32_e32 v23, v23, v27
	ds_write_b32 v81, v23 offset:30720
	s_waitcnt vmcnt(1)
	v_mul_f32_e32 v26, 0xbfb8aa3b, v24
	v_exp_f32_e32 v26, v26
	s_nop 0
	v_add_f32_e32 v26, 1.0, v26
	v_rcp_f32_e32 v26, v26
	s_nop 0
	v_mul_f32_e32 v24, v24, v26
	ds_write_b32 v81, v24 offset:32768
	s_waitcnt vmcnt(0)
	v_mul_f32_e32 v27, 0xbfb8aa3b, v25
	v_exp_f32_e32 v27, v27
	s_nop 0
	v_add_f32_e32 v27, 1.0, v27
	v_rcp_f32_e32 v27, v27
	s_nop 0
	v_mul_f32_e32 v25, v25, v27
	ds_write_b32 v81, v25 offset:34816
	s_mul_hi_i32 s14, s44, 0x38e38e39
	s_lshr_b32 s15, s14, 31
	s_ashr_i32 s14, s14, 4
	s_add_i32 s45, s14, s15
	s_mul_i32 s14, s45, 0x48
	s_sub_i32 s16, s44, s14
	v_mad_i64_i32 v[2:3], s[14:15], s45, v84, v[48:49]
	s_lshl_b32 s14, s16, 7
	s_ashr_i32 s15, s14, 31
	v_lshl_add_u64 v[2:3], s[14:15], 2, v[2:3]
	v_mov_b32_e32 v58, 0
	v_lshl_add_u64 v[56:57], v[2:3], 0, v[54:55]
	s_mov_b64 s[16:17], 0
	v_mov_b32_e32 v46, v78
	v_mov_b32_e32 v59, v58
	v_mov_b32_e32 v60, v58
	v_mov_b32_e32 v61, v58
	v_mov_b32_e32 v62, v58
	v_mov_b32_e32 v63, v58
	v_mov_b32_e32 v64, v58
	v_mov_b32_e32 v65, v58
	v_mov_b32_e32 v66, v58
	v_mov_b32_e32 v67, v58
	v_mov_b32_e32 v68, v58
	v_mov_b32_e32 v69, v58
	v_mov_b32_e32 v70, v58
	v_mov_b32_e32 v71, v58
	v_mov_b32_e32 v72, v58
	v_mov_b32_e32 v73, v58
	v_mov_b32_e32 v74, v58
	v_mov_b32_e32 v75, v58
	s_waitcnt lgkmcnt(0)
	s_barrier
	v_readfirstlane_b32 s46, v2
	v_readfirstlane_b32 s47, v3
	s_mov_b32 s50, 0
	s_nop 0
	s_mov_b64 s[48:49], s[46:47]
	global_load_dwordx2 v[160:161], v54, s[48:49]
	s_add_i32 s50, s50, 1
	s_min_u32 s51, s50, 0x7f
	s_mul_i32 s51, s51, 0x9000
	s_add_u32 s48, s46, s51
	s_addc_u32 s49, s47, 0
	global_load_dwordx2 v[162:163], v54, s[48:49]
	s_add_i32 s50, s50, 1
	s_min_u32 s51, s50, 0x7f
	s_mul_i32 s51, s51, 0x9000
	s_add_u32 s48, s46, s51
	s_addc_u32 s49, s47, 0
	global_load_dwordx2 v[164:165], v54, s[48:49]
	s_add_i32 s50, s50, 1
	s_min_u32 s51, s50, 0x7f
	s_mul_i32 s51, s51, 0x9000
	s_add_u32 s48, s46, s51
	s_addc_u32 s49, s47, 0
	global_load_dwordx2 v[166:167], v54, s[48:49]
	s_add_i32 s50, s50, 1
	s_min_u32 s51, s50, 0x7f
	s_mul_i32 s51, s51, 0x9000
	s_add_u32 s48, s46, s51
	s_addc_u32 s49, s47, 0
	global_load_dwordx2 v[168:169], v54, s[48:49]
	s_add_i32 s50, s50, 1
	s_min_u32 s51, s50, 0x7f
	s_mul_i32 s51, s51, 0x9000
	s_add_u32 s48, s46, s51
	s_addc_u32 s49, s47, 0
	global_load_dwordx2 v[170:171], v54, s[48:49]
	s_add_i32 s50, s50, 1
	s_min_u32 s51, s50, 0x7f
	s_mul_i32 s51, s51, 0x9000
	s_add_u32 s48, s46, s51
	s_addc_u32 s49, s47, 0
	global_load_dwordx2 v[172:173], v54, s[48:49]
	s_add_i32 s50, s50, 1
	s_min_u32 s51, s50, 0x7f
	s_mul_i32 s51, s51, 0x9000
	s_add_u32 s48, s46, s51
	s_addc_u32 s49, s47, 0
	global_load_dwordx2 v[174:175], v54, s[48:49]
	s_add_i32 s50, s50, 1
	s_min_u32 s51, s50, 0x7f
	s_mul_i32 s51, s51, 0x9000
	s_add_u32 s48, s46, s51
	s_addc_u32 s49, s47, 0
	global_load_dwordx2 v[176:177], v54, s[48:49]
	s_add_i32 s50, s50, 1
	s_min_u32 s51, s50, 0x7f
	s_mul_i32 s51, s51, 0x9000
	s_add_u32 s48, s46, s51
	s_addc_u32 s49, s47, 0
	global_load_dwordx2 v[178:179], v54, s[48:49]
	s_add_i32 s50, s50, 1
	s_min_u32 s51, s50, 0x7f
	s_mul_i32 s51, s51, 0x9000
	s_add_u32 s48, s46, s51
	s_addc_u32 s49, s47, 0
	global_load_dwordx2 v[180:181], v54, s[48:49]
	s_add_i32 s50, s50, 1
	s_min_u32 s51, s50, 0x7f
	s_mul_i32 s51, s51, 0x9000
	s_add_u32 s48, s46, s51
	s_addc_u32 s49, s47, 0
	global_load_dwordx2 v[182:183], v54, s[48:49]
	s_add_i32 s50, s50, 1
	s_min_u32 s51, s50, 0x7f
	s_mul_i32 s51, s51, 0x9000
	s_add_u32 s48, s46, s51
	s_addc_u32 s49, s47, 0
	global_load_dwordx2 v[184:185], v54, s[48:49]
	s_add_i32 s50, s50, 1
	s_min_u32 s51, s50, 0x7f
	s_mul_i32 s51, s51, 0x9000
	s_add_u32 s48, s46, s51
	s_addc_u32 s49, s47, 0
	global_load_dwordx2 v[186:187], v54, s[48:49]
	s_add_i32 s50, s50, 1
	s_min_u32 s51, s50, 0x7f
	s_mul_i32 s51, s51, 0x9000
	s_add_u32 s48, s46, s51
	s_addc_u32 s49, s47, 0
	global_load_dwordx2 v[188:189], v54, s[48:49]
	s_add_i32 s50, s50, 1
	s_min_u32 s51, s50, 0x7f
	s_mul_i32 s51, s51, 0x9000
	s_add_u32 s48, s46, s51
	s_addc_u32 s49, s47, 0
	global_load_dwordx2 v[190:191], v54, s[48:49]
	s_add_i32 s50, s50, 1
	s_min_u32 s51, s50, 0x7f
	s_mul_i32 s51, s51, 0x9000
	s_add_u32 s48, s46, s51
	s_addc_u32 s49, s47, 0
	global_load_dwordx2 v[192:193], v54, s[48:49]
	s_add_i32 s50, s50, 1
	s_min_u32 s51, s50, 0x7f
	s_mul_i32 s51, s51, 0x9000
	s_add_u32 s48, s46, s51
	s_addc_u32 s49, s47, 0
	global_load_dwordx2 v[194:195], v54, s[48:49]
	s_add_i32 s50, s50, 1
	s_min_u32 s51, s50, 0x7f
	s_mul_i32 s51, s51, 0x9000
	s_add_u32 s48, s46, s51
	s_addc_u32 s49, s47, 0
	global_load_dwordx2 v[196:197], v54, s[48:49]
	s_add_i32 s50, s50, 1
	s_min_u32 s51, s50, 0x7f
	s_mul_i32 s51, s51, 0x9000
	s_add_u32 s48, s46, s51
	s_addc_u32 s49, s47, 0
	global_load_dwordx2 v[198:199], v54, s[48:49]
	s_add_i32 s50, s50, 1
	s_min_u32 s51, s50, 0x7f
	s_mul_i32 s51, s51, 0x9000
	s_add_u32 s48, s46, s51
	s_addc_u32 s49, s47, 0
	global_load_dwordx2 v[200:201], v54, s[48:49]
	s_add_i32 s50, s50, 1
	s_min_u32 s51, s50, 0x7f
	s_mul_i32 s51, s51, 0x9000
	s_add_u32 s48, s46, s51
	s_addc_u32 s49, s47, 0
	global_load_dwordx2 v[202:203], v54, s[48:49]
	s_add_i32 s50, s50, 1
	s_min_u32 s51, s50, 0x7f
	s_mul_i32 s51, s51, 0x9000
	s_add_u32 s48, s46, s51
	s_addc_u32 s49, s47, 0
	global_load_dwordx2 v[204:205], v54, s[48:49]
	s_add_i32 s50, s50, 1
	s_min_u32 s51, s50, 0x7f
	s_mul_i32 s51, s51, 0x9000
	s_add_u32 s48, s46, s51
	s_addc_u32 s49, s47, 0
	global_load_dwordx2 v[206:207], v54, s[48:49]
	s_add_i32 s50, s50, 1
	s_min_u32 s51, s50, 0x7f
	s_mul_i32 s51, s51, 0x9000
	s_add_u32 s48, s46, s51
	s_addc_u32 s49, s47, 0
	s_mov_b32 s53, 0
.Lmy_gk:
	global_load_dwordx2 v[208:209], v54, s[48:49]
	s_add_i32 s50, s50, 1
	s_min_u32 s51, s50, 0x7f
	s_mul_i32 s51, s51, 0x9000
	s_add_u32 s48, s46, s51
	s_addc_u32 s49, s47, 0
	global_load_dwordx2 v[210:211], v54, s[48:49]
	s_add_i32 s50, s50, 1
	s_min_u32 s51, s50, 0x7f
	s_mul_i32 s51, s51, 0x9000
	s_add_u32 s48, s46, s51
	s_addc_u32 s49, s47, 0
	global_load_dwordx2 v[212:213], v54, s[48:49]
	s_add_i32 s50, s50, 1
	s_min_u32 s51, s50, 0x7f
	s_mul_i32 s51, s51, 0x9000
	s_add_u32 s48, s46, s51
	s_addc_u32 s49, s47, 0
	global_load_dwordx2 v[214:215], v54, s[48:49]
	s_add_i32 s50, s50, 1
	s_min_u32 s51, s50, 0x7f
	s_mul_i32 s51, s51, 0x9000
	s_add_u32 s48, s46, s51
	s_addc_u32 s49, s47, 0
	global_load_dwordx2 v[216:217], v54, s[48:49]
	s_add_i32 s50, s50, 1
	s_min_u32 s51, s50, 0x7f
	s_mul_i32 s51, s51, 0x9000
	s_add_u32 s48, s46, s51
	s_addc_u32 s49, s47, 0
	global_load_dwordx2 v[218:219], v54, s[48:49]
	s_add_i32 s50, s50, 1
	s_min_u32 s51, s50, 0x7f
	s_mul_i32 s51, s51, 0x9000
	s_add_u32 s48, s46, s51
	s_addc_u32 s49, s47, 0
	global_load_dwordx2 v[220:221], v54, s[48:49]
	s_add_i32 s50, s50, 1
	s_min_u32 s51, s50, 0x7f
	s_mul_i32 s51, s51, 0x9000
	s_add_u32 s48, s46, s51
	s_addc_u32 s49, s47, 0
	global_load_dwordx2 v[222:223], v54, s[48:49]
	s_add_i32 s50, s50, 1
	s_min_u32 s51, s50, 0x7f
	s_mul_i32 s51, s51, 0x9000
	s_add_u32 s48, s46, s51
	s_addc_u32 s49, s47, 0
	ds_read_b128 v[2:5], v46
	ds_read_b128 v[6:9], v46 offset:16
	ds_read_b128 v[10:13], v46 offset:4096
	ds_read_b128 v[14:17], v46 offset:4112
	ds_read_b128 v[18:21], v46 offset:8192
	ds_read_b128 v[22:25], v46 offset:8208
	ds_read_b128 v[26:29], v46 offset:12288
	ds_read_b128 v[30:33], v46 offset:12304
	ds_read_b128 v[34:37], v46 offset:16384
	ds_read_b128 v[38:41], v46 offset:16400
	ds_read_b128 v[86:89], v46 offset:20480
	ds_read_b128 v[90:93], v46 offset:20496
	ds_read_b128 v[94:97], v46 offset:24576
	ds_read_b128 v[98:101], v46 offset:24592
	ds_read_b128 v[102:105], v46 offset:28672
	ds_read_b128 v[106:109], v46 offset:28688
	ds_read_b128 v[110:113], v46 offset:32768
	ds_read_b128 v[114:117], v46 offset:32784
	v_add_u32_e32 v46, 32, v46
	s_waitcnt vmcnt(24)
	s_waitcnt lgkmcnt(0)
	v_pk_fma_f32 v[60:61], v[160:161], v[2:3], v[60:61] op_sel_hi:[1,0,1]
	v_pk_fma_f32 v[62:63], v[160:161], v[10:11], v[62:63] op_sel_hi:[1,0,1]
	v_pk_fma_f32 v[64:65], v[160:161], v[18:19], v[64:65] op_sel_hi:[1,0,1]
	v_pk_fma_f32 v[66:67], v[160:161], v[26:27], v[66:67] op_sel_hi:[1,0,1]
	v_pk_fma_f32 v[68:69], v[160:161], v[34:35], v[68:69] op_sel_hi:[1,0,1]
	v_pk_fma_f32 v[70:71], v[160:161], v[86:87], v[70:71] op_sel_hi:[1,0,1]
	v_pk_fma_f32 v[72:73], v[160:161], v[94:95], v[72:73] op_sel_hi:[1,0,1]
	v_pk_fma_f32 v[74:75], v[160:161], v[102:103], v[74:75] op_sel_hi:[1,0,1]
	v_pk_fma_f32 v[58:59], v[160:161], v[110:111], v[58:59] op_sel_hi:[1,0,1]
	v_pk_fma_f32 v[60:61], v[162:163], v[2:3], v[60:61] op_sel:[0,1,0]
	v_pk_fma_f32 v[62:63], v[162:163], v[10:11], v[62:63] op_sel:[0,1,0]
	v_pk_fma_f32 v[64:65], v[162:163], v[18:19], v[64:65] op_sel:[0,1,0]
	v_pk_fma_f32 v[66:67], v[162:163], v[26:27], v[66:67] op_sel:[0,1,0]
	v_pk_fma_f32 v[68:69], v[162:163], v[34:35], v[68:69] op_sel:[0,1,0]
	v_pk_fma_f32 v[70:71], v[162:163], v[86:87], v[70:71] op_sel:[0,1,0]
	v_pk_fma_f32 v[72:73], v[162:163], v[94:95], v[72:73] op_sel:[0,1,0]
	v_pk_fma_f32 v[74:75], v[162:163], v[102:103], v[74:75] op_sel:[0,1,0]
	v_pk_fma_f32 v[58:59], v[162:163], v[110:111], v[58:59] op_sel:[0,1,0]
	v_pk_fma_f32 v[60:61], v[164:165], v[4:5], v[60:61] op_sel_hi:[1,0,1]
	v_pk_fma_f32 v[62:63], v[164:165], v[12:13], v[62:63] op_sel_hi:[1,0,1]
	v_pk_fma_f32 v[64:65], v[164:165], v[20:21], v[64:65] op_sel_hi:[1,0,1]
	v_pk_fma_f32 v[66:67], v[164:165], v[28:29], v[66:67] op_sel_hi:[1,0,1]
	v_pk_fma_f32 v[68:69], v[164:165], v[36:37], v[68:69] op_sel_hi:[1,0,1]
	v_pk_fma_f32 v[70:71], v[164:165], v[88:89], v[70:71] op_sel_hi:[1,0,1]
	v_pk_fma_f32 v[72:73], v[164:165], v[96:97], v[72:73] op_sel_hi:[1,0,1]
	v_pk_fma_f32 v[74:75], v[164:165], v[104:105], v[74:75] op_sel_hi:[1,0,1]
	v_pk_fma_f32 v[58:59], v[164:165], v[112:113], v[58:59] op_sel_hi:[1,0,1]
	v_pk_fma_f32 v[60:61], v[166:167], v[4:5], v[60:61] op_sel:[0,1,0]
	v_pk_fma_f32 v[62:63], v[166:167], v[12:13], v[62:63] op_sel:[0,1,0]
	v_pk_fma_f32 v[64:65], v[166:167], v[20:21], v[64:65] op_sel:[0,1,0]
	v_pk_fma_f32 v[66:67], v[166:167], v[28:29], v[66:67] op_sel:[0,1,0]
	v_pk_fma_f32 v[68:69], v[166:167], v[36:37], v[68:69] op_sel:[0,1,0]
	v_pk_fma_f32 v[70:71], v[166:167], v[88:89], v[70:71] op_sel:[0,1,0]
	v_pk_fma_f32 v[72:73], v[166:167], v[96:97], v[72:73] op_sel:[0,1,0]
	v_pk_fma_f32 v[74:75], v[166:167], v[104:105], v[74:75] op_sel:[0,1,0]
	v_pk_fma_f32 v[58:59], v[166:167], v[112:113], v[58:59] op_sel:[0,1,0]
	v_pk_fma_f32 v[60:61], v[168:169], v[6:7], v[60:61] op_sel_hi:[1,0,1]
	v_pk_fma_f32 v[62:63], v[168:169], v[14:15], v[62:63] op_sel_hi:[1,0,1]
	v_pk_fma_f32 v[64:65], v[168:169], v[22:23], v[64:65] op_sel_hi:[1,0,1]
	v_pk_fma_f32 v[66:67], v[168:169], v[30:31], v[66:67] op_sel_hi:[1,0,1]
	v_pk_fma_f32 v[68:69], v[168:169], v[38:39], v[68:69] op_sel_hi:[1,0,1]
	v_pk_fma_f32 v[70:71], v[168:169], v[90:91], v[70:71] op_sel_hi:[1,0,1]
	v_pk_fma_f32 v[72:73], v[168:169], v[98:99], v[72:73] op_sel_hi:[1,0,1]
	v_pk_fma_f32 v[74:75], v[168:169], v[106:107], v[74:75] op_sel_hi:[1,0,1]
	v_pk_fma_f32 v[58:59], v[168:169], v[114:115], v[58:59] op_sel_hi:[1,0,1]
	v_pk_fma_f32 v[60:61], v[170:171], v[6:7], v[60:61] op_sel:[0,1,0]
	v_pk_fma_f32 v[62:63], v[170:171], v[14:15], v[62:63] op_sel:[0,1,0]
	v_pk_fma_f32 v[64:65], v[170:171], v[22:23], v[64:65] op_sel:[0,1,0]
	v_pk_fma_f32 v[66:67], v[170:171], v[30:31], v[66:67] op_sel:[0,1,0]
	v_pk_fma_f32 v[68:69], v[170:171], v[38:39], v[68:69] op_sel:[0,1,0]
	v_pk_fma_f32 v[70:71], v[170:171], v[90:91], v[70:71] op_sel:[0,1,0]
	v_pk_fma_f32 v[72:73], v[170:171], v[98:99], v[72:73] op_sel:[0,1,0]
	v_pk_fma_f32 v[74:75], v[170:171], v[106:107], v[74:75] op_sel:[0,1,0]
	v_pk_fma_f32 v[58:59], v[170:171], v[114:115], v[58:59] op_sel:[0,1,0]
	v_pk_fma_f32 v[60:61], v[172:173], v[8:9], v[60:61] op_sel_hi:[1,0,1]
	v_pk_fma_f32 v[62:63], v[172:173], v[16:17], v[62:63] op_sel_hi:[1,0,1]
	v_pk_fma_f32 v[64:65], v[172:173], v[24:25], v[64:65] op_sel_hi:[1,0,1]
	v_pk_fma_f32 v[66:67], v[172:173], v[32:33], v[66:67] op_sel_hi:[1,0,1]
	v_pk_fma_f32 v[68:69], v[172:173], v[40:41], v[68:69] op_sel_hi:[1,0,1]
	v_pk_fma_f32 v[70:71], v[172:173], v[92:93], v[70:71] op_sel_hi:[1,0,1]
	v_pk_fma_f32 v[72:73], v[172:173], v[100:101], v[72:73] op_sel_hi:[1,0,1]
	v_pk_fma_f32 v[74:75], v[172:173], v[108:109], v[74:75] op_sel_hi:[1,0,1]
	v_pk_fma_f32 v[58:59], v[172:173], v[116:117], v[58:59] op_sel_hi:[1,0,1]
	v_pk_fma_f32 v[60:61], v[174:175], v[8:9], v[60:61] op_sel:[0,1,0]
	v_pk_fma_f32 v[62:63], v[174:175], v[16:17], v[62:63] op_sel:[0,1,0]
	v_pk_fma_f32 v[64:65], v[174:175], v[24:25], v[64:65] op_sel:[0,1,0]
	v_pk_fma_f32 v[66:67], v[174:175], v[32:33], v[66:67] op_sel:[0,1,0]
	v_pk_fma_f32 v[68:69], v[174:175], v[40:41], v[68:69] op_sel:[0,1,0]
	v_pk_fma_f32 v[70:71], v[174:175], v[92:93], v[70:71] op_sel:[0,1,0]
	v_pk_fma_f32 v[72:73], v[174:175], v[100:101], v[72:73] op_sel:[0,1,0]
	v_pk_fma_f32 v[74:75], v[174:175], v[108:109], v[74:75] op_sel:[0,1,0]
	v_pk_fma_f32 v[58:59], v[174:175], v[116:117], v[58:59] op_sel:[0,1,0]
	global_load_dwordx2 v[160:161], v54, s[48:49]
	s_add_i32 s50, s50, 1
	s_min_u32 s51, s50, 0x7f
	s_mul_i32 s51, s51, 0x9000
	s_add_u32 s48, s46, s51
	s_addc_u32 s49, s47, 0
	global_load_dwordx2 v[162:163], v54, s[48:49]
	s_add_i32 s50, s50, 1
	s_min_u32 s51, s50, 0x7f
	s_mul_i32 s51, s51, 0x9000
	s_add_u32 s48, s46, s51
	s_addc_u32 s49, s47, 0
	global_load_dwordx2 v[164:165], v54, s[48:49]
	s_add_i32 s50, s50, 1
	s_min_u32 s51, s50, 0x7f
	s_mul_i32 s51, s51, 0x9000
	s_add_u32 s48, s46, s51
	s_addc_u32 s49, s47, 0
	global_load_dwordx2 v[166:167], v54, s[48:49]
	s_add_i32 s50, s50, 1
	s_min_u32 s51, s50, 0x7f
	s_mul_i32 s51, s51, 0x9000
	s_add_u32 s48, s46, s51
	s_addc_u32 s49, s47, 0
	global_load_dwordx2 v[168:169], v54, s[48:49]
	s_add_i32 s50, s50, 1
	s_min_u32 s51, s50, 0x7f
	s_mul_i32 s51, s51, 0x9000
	s_add_u32 s48, s46, s51
	s_addc_u32 s49, s47, 0
	global_load_dwordx2 v[170:171], v54, s[48:49]
	s_add_i32 s50, s50, 1
	s_min_u32 s51, s50, 0x7f
	s_mul_i32 s51, s51, 0x9000
	s_add_u32 s48, s46, s51
	s_addc_u32 s49, s47, 0
	global_load_dwordx2 v[172:173], v54, s[48:49]
	s_add_i32 s50, s50, 1
	s_min_u32 s51, s50, 0x7f
	s_mul_i32 s51, s51, 0x9000
	s_add_u32 s48, s46, s51
	s_addc_u32 s49, s47, 0
	global_load_dwordx2 v[174:175], v54, s[48:49]
	s_add_i32 s50, s50, 1
	s_min_u32 s51, s50, 0x7f
	s_mul_i32 s51, s51, 0x9000
	s_add_u32 s48, s46, s51
	s_addc_u32 s49, s47, 0
	ds_read_b128 v[2:5], v46
	ds_read_b128 v[6:9], v46 offset:16
	ds_read_b128 v[10:13], v46 offset:4096
	ds_read_b128 v[14:17], v46 offset:4112
	ds_read_b128 v[18:21], v46 offset:8192
	ds_read_b128 v[22:25], v46 offset:8208
	ds_read_b128 v[26:29], v46 offset:12288
	ds_read_b128 v[30:33], v46 offset:12304
	ds_read_b128 v[34:37], v46 offset:16384
	ds_read_b128 v[38:41], v46 offset:16400
	ds_read_b128 v[86:89], v46 offset:20480
	ds_read_b128 v[90:93], v46 offset:20496
	ds_read_b128 v[94:97], v46 offset:24576
	ds_read_b128 v[98:101], v46 offset:24592
	ds_read_b128 v[102:105], v46 offset:28672
	ds_read_b128 v[106:109], v46 offset:28688
	ds_read_b128 v[110:113], v46 offset:32768
	ds_read_b128 v[114:117], v46 offset:32784
	v_add_u32_e32 v46, 32, v46
	s_waitcnt vmcnt(24)
	s_waitcnt lgkmcnt(0)
	v_pk_fma_f32 v[60:61], v[176:177], v[2:3], v[60:61] op_sel_hi:[1,0,1]
	v_pk_fma_f32 v[62:63], v[176:177], v[10:11], v[62:63] op_sel_hi:[1,0,1]
	v_pk_fma_f32 v[64:65], v[176:177], v[18:19], v[64:65] op_sel_hi:[1,0,1]
	v_pk_fma_f32 v[66:67], v[176:177], v[26:27], v[66:67] op_sel_hi:[1,0,1]
	v_pk_fma_f32 v[68:69], v[176:177], v[34:35], v[68:69] op_sel_hi:[1,0,1]
	v_pk_fma_f32 v[70:71], v[176:177], v[86:87], v[70:71] op_sel_hi:[1,0,1]
	v_pk_fma_f32 v[72:73], v[176:177], v[94:95], v[72:73] op_sel_hi:[1,0,1]
	v_pk_fma_f32 v[74:75], v[176:177], v[102:103], v[74:75] op_sel_hi:[1,0,1]
	v_pk_fma_f32 v[58:59], v[176:177], v[110:111], v[58:59] op_sel_hi:[1,0,1]
	v_pk_fma_f32 v[60:61], v[178:179], v[2:3], v[60:61] op_sel:[0,1,0]
	v_pk_fma_f32 v[62:63], v[178:179], v[10:11], v[62:63] op_sel:[0,1,0]
	v_pk_fma_f32 v[64:65], v[178:179], v[18:19], v[64:65] op_sel:[0,1,0]
	v_pk_fma_f32 v[66:67], v[178:179], v[26:27], v[66:67] op_sel:[0,1,0]
	v_pk_fma_f32 v[68:69], v[178:179], v[34:35], v[68:69] op_sel:[0,1,0]
	v_pk_fma_f32 v[70:71], v[178:179], v[86:87], v[70:71] op_sel:[0,1,0]
	v_pk_fma_f32 v[72:73], v[178:179], v[94:95], v[72:73] op_sel:[0,1,0]
	v_pk_fma_f32 v[74:75], v[178:179], v[102:103], v[74:75] op_sel:[0,1,0]
	v_pk_fma_f32 v[58:59], v[178:179], v[110:111], v[58:59] op_sel:[0,1,0]
	v_pk_fma_f32 v[60:61], v[180:181], v[4:5], v[60:61] op_sel_hi:[1,0,1]
	v_pk_fma_f32 v[62:63], v[180:181], v[12:13], v[62:63] op_sel_hi:[1,0,1]
	v_pk_fma_f32 v[64:65], v[180:181], v[20:21], v[64:65] op_sel_hi:[1,0,1]
	v_pk_fma_f32 v[66:67], v[180:181], v[28:29], v[66:67] op_sel_hi:[1,0,1]
	v_pk_fma_f32 v[68:69], v[180:181], v[36:37], v[68:69] op_sel_hi:[1,0,1]
	v_pk_fma_f32 v[70:71], v[180:181], v[88:89], v[70:71] op_sel_hi:[1,0,1]
	v_pk_fma_f32 v[72:73], v[180:181], v[96:97], v[72:73] op_sel_hi:[1,0,1]
	v_pk_fma_f32 v[74:75], v[180:181], v[104:105], v[74:75] op_sel_hi:[1,0,1]
	v_pk_fma_f32 v[58:59], v[180:181], v[112:113], v[58:59] op_sel_hi:[1,0,1]
	v_pk_fma_f32 v[60:61], v[182:183], v[4:5], v[60:61] op_sel:[0,1,0]
	v_pk_fma_f32 v[62:63], v[182:183], v[12:13], v[62:63] op_sel:[0,1,0]
	v_pk_fma_f32 v[64:65], v[182:183], v[20:21], v[64:65] op_sel:[0,1,0]
	v_pk_fma_f32 v[66:67], v[182:183], v[28:29], v[66:67] op_sel:[0,1,0]
	v_pk_fma_f32 v[68:69], v[182:183], v[36:37], v[68:69] op_sel:[0,1,0]
	v_pk_fma_f32 v[70:71], v[182:183], v[88:89], v[70:71] op_sel:[0,1,0]
	v_pk_fma_f32 v[72:73], v[182:183], v[96:97], v[72:73] op_sel:[0,1,0]
	v_pk_fma_f32 v[74:75], v[182:183], v[104:105], v[74:75] op_sel:[0,1,0]
	v_pk_fma_f32 v[58:59], v[182:183], v[112:113], v[58:59] op_sel:[0,1,0]
	v_pk_fma_f32 v[60:61], v[184:185], v[6:7], v[60:61] op_sel_hi:[1,0,1]
	v_pk_fma_f32 v[62:63], v[184:185], v[14:15], v[62:63] op_sel_hi:[1,0,1]
	v_pk_fma_f32 v[64:65], v[184:185], v[22:23], v[64:65] op_sel_hi:[1,0,1]
	v_pk_fma_f32 v[66:67], v[184:185], v[30:31], v[66:67] op_sel_hi:[1,0,1]
	v_pk_fma_f32 v[68:69], v[184:185], v[38:39], v[68:69] op_sel_hi:[1,0,1]
	v_pk_fma_f32 v[70:71], v[184:185], v[90:91], v[70:71] op_sel_hi:[1,0,1]
	v_pk_fma_f32 v[72:73], v[184:185], v[98:99], v[72:73] op_sel_hi:[1,0,1]
	v_pk_fma_f32 v[74:75], v[184:185], v[106:107], v[74:75] op_sel_hi:[1,0,1]
	v_pk_fma_f32 v[58:59], v[184:185], v[114:115], v[58:59] op_sel_hi:[1,0,1]
	v_pk_fma_f32 v[60:61], v[186:187], v[6:7], v[60:61] op_sel:[0,1,0]
	v_pk_fma_f32 v[62:63], v[186:187], v[14:15], v[62:63] op_sel:[0,1,0]
	v_pk_fma_f32 v[64:65], v[186:187], v[22:23], v[64:65] op_sel:[0,1,0]
	v_pk_fma_f32 v[66:67], v[186:187], v[30:31], v[66:67] op_sel:[0,1,0]
	v_pk_fma_f32 v[68:69], v[186:187], v[38:39], v[68:69] op_sel:[0,1,0]
	v_pk_fma_f32 v[70:71], v[186:187], v[90:91], v[70:71] op_sel:[0,1,0]
	v_pk_fma_f32 v[72:73], v[186:187], v[98:99], v[72:73] op_sel:[0,1,0]
	v_pk_fma_f32 v[74:75], v[186:187], v[106:107], v[74:75] op_sel:[0,1,0]
	v_pk_fma_f32 v[58:59], v[186:187], v[114:115], v[58:59] op_sel:[0,1,0]
	v_pk_fma_f32 v[60:61], v[188:189], v[8:9], v[60:61] op_sel_hi:[1,0,1]
	v_pk_fma_f32 v[62:63], v[188:189], v[16:17], v[62:63] op_sel_hi:[1,0,1]
	v_pk_fma_f32 v[64:65], v[188:189], v[24:25], v[64:65] op_sel_hi:[1,0,1]
	v_pk_fma_f32 v[66:67], v[188:189], v[32:33], v[66:67] op_sel_hi:[1,0,1]
	v_pk_fma_f32 v[68:69], v[188:189], v[40:41], v[68:69] op_sel_hi:[1,0,1]
	v_pk_fma_f32 v[70:71], v[188:189], v[92:93], v[70:71] op_sel_hi:[1,0,1]
	v_pk_fma_f32 v[72:73], v[188:189], v[100:101], v[72:73] op_sel_hi:[1,0,1]
	v_pk_fma_f32 v[74:75], v[188:189], v[108:109], v[74:75] op_sel_hi:[1,0,1]
	v_pk_fma_f32 v[58:59], v[188:189], v[116:117], v[58:59] op_sel_hi:[1,0,1]
	v_pk_fma_f32 v[60:61], v[190:191], v[8:9], v[60:61] op_sel:[0,1,0]
	v_pk_fma_f32 v[62:63], v[190:191], v[16:17], v[62:63] op_sel:[0,1,0]
	v_pk_fma_f32 v[64:65], v[190:191], v[24:25], v[64:65] op_sel:[0,1,0]
	v_pk_fma_f32 v[66:67], v[190:191], v[32:33], v[66:67] op_sel:[0,1,0]
	v_pk_fma_f32 v[68:69], v[190:191], v[40:41], v[68:69] op_sel:[0,1,0]
	v_pk_fma_f32 v[70:71], v[190:191], v[92:93], v[70:71] op_sel:[0,1,0]
	v_pk_fma_f32 v[72:73], v[190:191], v[100:101], v[72:73] op_sel:[0,1,0]
	v_pk_fma_f32 v[74:75], v[190:191], v[108:109], v[74:75] op_sel:[0,1,0]
	v_pk_fma_f32 v[58:59], v[190:191], v[116:117], v[58:59] op_sel:[0,1,0]
	global_load_dwordx2 v[176:177], v54, s[48:49]
	s_add_i32 s50, s50, 1
	s_min_u32 s51, s50, 0x7f
	s_mul_i32 s51, s51, 0x9000
	s_add_u32 s48, s46, s51
	s_addc_u32 s49, s47, 0
	global_load_dwordx2 v[178:179], v54, s[48:49]
	s_add_i32 s50, s50, 1
	s_min_u32 s51, s50, 0x7f
	s_mul_i32 s51, s51, 0x9000
	s_add_u32 s48, s46, s51
	s_addc_u32 s49, s47, 0
	global_load_dwordx2 v[180:181], v54, s[48:49]
	s_add_i32 s50, s50, 1
	s_min_u32 s51, s50, 0x7f
	s_mul_i32 s51, s51, 0x9000
	s_add_u32 s48, s46, s51
	s_addc_u32 s49, s47, 0
	global_load_dwordx2 v[182:183], v54, s[48:49]
	s_add_i32 s50, s50, 1
	s_min_u32 s51, s50, 0x7f
	s_mul_i32 s51, s51, 0x9000
	s_add_u32 s48, s46, s51
	s_addc_u32 s49, s47, 0
	global_load_dwordx2 v[184:185], v54, s[48:49]
	s_add_i32 s50, s50, 1
	s_min_u32 s51, s50, 0x7f
	s_mul_i32 s51, s51, 0x9000
	s_add_u32 s48, s46, s51
	s_addc_u32 s49, s47, 0
	global_load_dwordx2 v[186:187], v54, s[48:49]
	s_add_i32 s50, s50, 1
	s_min_u32 s51, s50, 0x7f
	s_mul_i32 s51, s51, 0x9000
	s_add_u32 s48, s46, s51
	s_addc_u32 s49, s47, 0
	global_load_dwordx2 v[188:189], v54, s[48:49]
	s_add_i32 s50, s50, 1
	s_min_u32 s51, s50, 0x7f
	s_mul_i32 s51, s51, 0x9000
	s_add_u32 s48, s46, s51
	s_addc_u32 s49, s47, 0
	global_load_dwordx2 v[190:191], v54, s[48:49]
	s_add_i32 s50, s50, 1
	s_min_u32 s51, s50, 0x7f
	s_mul_i32 s51, s51, 0x9000
	s_add_u32 s48, s46, s51
	s_addc_u32 s49, s47, 0
	ds_read_b128 v[2:5], v46
	ds_read_b128 v[6:9], v46 offset:16
	ds_read_b128 v[10:13], v46 offset:4096
	ds_read_b128 v[14:17], v46 offset:4112
	ds_read_b128 v[18:21], v46 offset:8192
	ds_read_b128 v[22:25], v46 offset:8208
	ds_read_b128 v[26:29], v46 offset:12288
	ds_read_b128 v[30:33], v46 offset:12304
	ds_read_b128 v[34:37], v46 offset:16384
	ds_read_b128 v[38:41], v46 offset:16400
	ds_read_b128 v[86:89], v46 offset:20480
	ds_read_b128 v[90:93], v46 offset:20496
	ds_read_b128 v[94:97], v46 offset:24576
	ds_read_b128 v[98:101], v46 offset:24592
	ds_read_b128 v[102:105], v46 offset:28672
	ds_read_b128 v[106:109], v46 offset:28688
	ds_read_b128 v[110:113], v46 offset:32768
	ds_read_b128 v[114:117], v46 offset:32784
	v_add_u32_e32 v46, 32, v46
	s_waitcnt vmcnt(24)
	s_waitcnt lgkmcnt(0)
	v_pk_fma_f32 v[60:61], v[192:193], v[2:3], v[60:61] op_sel_hi:[1,0,1]
	v_pk_fma_f32 v[62:63], v[192:193], v[10:11], v[62:63] op_sel_hi:[1,0,1]
	v_pk_fma_f32 v[64:65], v[192:193], v[18:19], v[64:65] op_sel_hi:[1,0,1]
	v_pk_fma_f32 v[66:67], v[192:193], v[26:27], v[66:67] op_sel_hi:[1,0,1]
	v_pk_fma_f32 v[68:69], v[192:193], v[34:35], v[68:69] op_sel_hi:[1,0,1]
	v_pk_fma_f32 v[70:71], v[192:193], v[86:87], v[70:71] op_sel_hi:[1,0,1]
	v_pk_fma_f32 v[72:73], v[192:193], v[94:95], v[72:73] op_sel_hi:[1,0,1]
	v_pk_fma_f32 v[74:75], v[192:193], v[102:103], v[74:75] op_sel_hi:[1,0,1]
	v_pk_fma_f32 v[58:59], v[192:193], v[110:111], v[58:59] op_sel_hi:[1,0,1]
	v_pk_fma_f32 v[60:61], v[194:195], v[2:3], v[60:61] op_sel:[0,1,0]
	v_pk_fma_f32 v[62:63], v[194:195], v[10:11], v[62:63] op_sel:[0,1,0]
	v_pk_fma_f32 v[64:65], v[194:195], v[18:19], v[64:65] op_sel:[0,1,0]
	v_pk_fma_f32 v[66:67], v[194:195], v[26:27], v[66:67] op_sel:[0,1,0]
	v_pk_fma_f32 v[68:69], v[194:195], v[34:35], v[68:69] op_sel:[0,1,0]
	v_pk_fma_f32 v[70:71], v[194:195], v[86:87], v[70:71] op_sel:[0,1,0]
	v_pk_fma_f32 v[72:73], v[194:195], v[94:95], v[72:73] op_sel:[0,1,0]
	v_pk_fma_f32 v[74:75], v[194:195], v[102:103], v[74:75] op_sel:[0,1,0]
	v_pk_fma_f32 v[58:59], v[194:195], v[110:111], v[58:59] op_sel:[0,1,0]
	v_pk_fma_f32 v[60:61], v[196:197], v[4:5], v[60:61] op_sel_hi:[1,0,1]
	v_pk_fma_f32 v[62:63], v[196:197], v[12:13], v[62:63] op_sel_hi:[1,0,1]
	v_pk_fma_f32 v[64:65], v[196:197], v[20:21], v[64:65] op_sel_hi:[1,0,1]
	v_pk_fma_f32 v[66:67], v[196:197], v[28:29], v[66:67] op_sel_hi:[1,0,1]
	v_pk_fma_f32 v[68:69], v[196:197], v[36:37], v[68:69] op_sel_hi:[1,0,1]
	v_pk_fma_f32 v[70:71], v[196:197], v[88:89], v[70:71] op_sel_hi:[1,0,1]
	v_pk_fma_f32 v[72:73], v[196:197], v[96:97], v[72:73] op_sel_hi:[1,0,1]
	v_pk_fma_f32 v[74:75], v[196:197], v[104:105], v[74:75] op_sel_hi:[1,0,1]
	v_pk_fma_f32 v[58:59], v[196:197], v[112:113], v[58:59] op_sel_hi:[1,0,1]
	v_pk_fma_f32 v[60:61], v[198:199], v[4:5], v[60:61] op_sel:[0,1,0]
	v_pk_fma_f32 v[62:63], v[198:199], v[12:13], v[62:63] op_sel:[0,1,0]
	v_pk_fma_f32 v[64:65], v[198:199], v[20:21], v[64:65] op_sel:[0,1,0]
	v_pk_fma_f32 v[66:67], v[198:199], v[28:29], v[66:67] op_sel:[0,1,0]
	v_pk_fma_f32 v[68:69], v[198:199], v[36:37], v[68:69] op_sel:[0,1,0]
	v_pk_fma_f32 v[70:71], v[198:199], v[88:89], v[70:71] op_sel:[0,1,0]
	v_pk_fma_f32 v[72:73], v[198:199], v[96:97], v[72:73] op_sel:[0,1,0]
	v_pk_fma_f32 v[74:75], v[198:199], v[104:105], v[74:75] op_sel:[0,1,0]
	v_pk_fma_f32 v[58:59], v[198:199], v[112:113], v[58:59] op_sel:[0,1,0]
	v_pk_fma_f32 v[60:61], v[200:201], v[6:7], v[60:61] op_sel_hi:[1,0,1]
	v_pk_fma_f32 v[62:63], v[200:201], v[14:15], v[62:63] op_sel_hi:[1,0,1]
	v_pk_fma_f32 v[64:65], v[200:201], v[22:23], v[64:65] op_sel_hi:[1,0,1]
	v_pk_fma_f32 v[66:67], v[200:201], v[30:31], v[66:67] op_sel_hi:[1,0,1]
	v_pk_fma_f32 v[68:69], v[200:201], v[38:39], v[68:69] op_sel_hi:[1,0,1]
	v_pk_fma_f32 v[70:71], v[200:201], v[90:91], v[70:71] op_sel_hi:[1,0,1]
	v_pk_fma_f32 v[72:73], v[200:201], v[98:99], v[72:73] op_sel_hi:[1,0,1]
	v_pk_fma_f32 v[74:75], v[200:201], v[106:107], v[74:75] op_sel_hi:[1,0,1]
	v_pk_fma_f32 v[58:59], v[200:201], v[114:115], v[58:59] op_sel_hi:[1,0,1]
	v_pk_fma_f32 v[60:61], v[202:203], v[6:7], v[60:61] op_sel:[0,1,0]
	v_pk_fma_f32 v[62:63], v[202:203], v[14:15], v[62:63] op_sel:[0,1,0]
	v_pk_fma_f32 v[64:65], v[202:203], v[22:23], v[64:65] op_sel:[0,1,0]
	v_pk_fma_f32 v[66:67], v[202:203], v[30:31], v[66:67] op_sel:[0,1,0]
	v_pk_fma_f32 v[68:69], v[202:203], v[38:39], v[68:69] op_sel:[0,1,0]
	v_pk_fma_f32 v[70:71], v[202:203], v[90:91], v[70:71] op_sel:[0,1,0]
	v_pk_fma_f32 v[72:73], v[202:203], v[98:99], v[72:73] op_sel:[0,1,0]
	v_pk_fma_f32 v[74:75], v[202:203], v[106:107], v[74:75] op_sel:[0,1,0]
	v_pk_fma_f32 v[58:59], v[202:203], v[114:115], v[58:59] op_sel:[0,1,0]
	v_pk_fma_f32 v[60:61], v[204:205], v[8:9], v[60:61] op_sel_hi:[1,0,1]
	v_pk_fma_f32 v[62:63], v[204:205], v[16:17], v[62:63] op_sel_hi:[1,0,1]
	v_pk_fma_f32 v[64:65], v[204:205], v[24:25], v[64:65] op_sel_hi:[1,0,1]
	v_pk_fma_f32 v[66:67], v[204:205], v[32:33], v[66:67] op_sel_hi:[1,0,1]
	v_pk_fma_f32 v[68:69], v[204:205], v[40:41], v[68:69] op_sel_hi:[1,0,1]
	v_pk_fma_f32 v[70:71], v[204:205], v[92:93], v[70:71] op_sel_hi:[1,0,1]
	v_pk_fma_f32 v[72:73], v[204:205], v[100:101], v[72:73] op_sel_hi:[1,0,1]
	v_pk_fma_f32 v[74:75], v[204:205], v[108:109], v[74:75] op_sel_hi:[1,0,1]
	v_pk_fma_f32 v[58:59], v[204:205], v[116:117], v[58:59] op_sel_hi:[1,0,1]
	v_pk_fma_f32 v[60:61], v[206:207], v[8:9], v[60:61] op_sel:[0,1,0]
	v_pk_fma_f32 v[62:63], v[206:207], v[16:17], v[62:63] op_sel:[0,1,0]
	v_pk_fma_f32 v[64:65], v[206:207], v[24:25], v[64:65] op_sel:[0,1,0]
	v_pk_fma_f32 v[66:67], v[206:207], v[32:33], v[66:67] op_sel:[0,1,0]
	v_pk_fma_f32 v[68:69], v[206:207], v[40:41], v[68:69] op_sel:[0,1,0]
	v_pk_fma_f32 v[70:71], v[206:207], v[92:93], v[70:71] op_sel:[0,1,0]
	v_pk_fma_f32 v[72:73], v[206:207], v[100:101], v[72:73] op_sel:[0,1,0]
	v_pk_fma_f32 v[74:75], v[206:207], v[108:109], v[74:75] op_sel:[0,1,0]
	v_pk_fma_f32 v[58:59], v[206:207], v[116:117], v[58:59] op_sel:[0,1,0]
	global_load_dwordx2 v[192:193], v54, s[48:49]
	s_add_i32 s50, s50, 1
	s_min_u32 s51, s50, 0x7f
	s_mul_i32 s51, s51, 0x9000
	s_add_u32 s48, s46, s51
	s_addc_u32 s49, s47, 0
	global_load_dwordx2 v[194:195], v54, s[48:49]
	s_add_i32 s50, s50, 1
	s_min_u32 s51, s50, 0x7f
	s_mul_i32 s51, s51, 0x9000
	s_add_u32 s48, s46, s51
	s_addc_u32 s49, s47, 0
	global_load_dwordx2 v[196:197], v54, s[48:49]
	s_add_i32 s50, s50, 1
	s_min_u32 s51, s50, 0x7f
	s_mul_i32 s51, s51, 0x9000
	s_add_u32 s48, s46, s51
	s_addc_u32 s49, s47, 0
	global_load_dwordx2 v[198:199], v54, s[48:49]
	s_add_i32 s50, s50, 1
	s_min_u32 s51, s50, 0x7f
	s_mul_i32 s51, s51, 0x9000
	s_add_u32 s48, s46, s51
	s_addc_u32 s49, s47, 0
	global_load_dwordx2 v[200:201], v54, s[48:49]
	s_add_i32 s50, s50, 1
	s_min_u32 s51, s50, 0x7f
	s_mul_i32 s51, s51, 0x9000
	s_add_u32 s48, s46, s51
	s_addc_u32 s49, s47, 0
	global_load_dwordx2 v[202:203], v54, s[48:49]
	s_add_i32 s50, s50, 1
	s_min_u32 s51, s50, 0x7f
	s_mul_i32 s51, s51, 0x9000
	s_add_u32 s48, s46, s51
	s_addc_u32 s49, s47, 0
	global_load_dwordx2 v[204:205], v54, s[48:49]
	s_add_i32 s50, s50, 1
	s_min_u32 s51, s50, 0x7f
	s_mul_i32 s51, s51, 0x9000
	s_add_u32 s48, s46, s51
	s_addc_u32 s49, s47, 0
	global_load_dwordx2 v[206:207], v54, s[48:49]
	s_add_i32 s50, s50, 1
	s_min_u32 s51, s50, 0x7f
	s_mul_i32 s51, s51, 0x9000
	s_add_u32 s48, s46, s51
	s_addc_u32 s49, s47, 0
	ds_read_b128 v[2:5], v46
	ds_read_b128 v[6:9], v46 offset:16
	ds_read_b128 v[10:13], v46 offset:4096
	ds_read_b128 v[14:17], v46 offset:4112
	ds_read_b128 v[18:21], v46 offset:8192
	ds_read_b128 v[22:25], v46 offset:8208
	ds_read_b128 v[26:29], v46 offset:12288
	ds_read_b128 v[30:33], v46 offset:12304
	ds_read_b128 v[34:37], v46 offset:16384
	ds_read_b128 v[38:41], v46 offset:16400
	ds_read_b128 v[86:89], v46 offset:20480
	ds_read_b128 v[90:93], v46 offset:20496
	ds_read_b128 v[94:97], v46 offset:24576
	ds_read_b128 v[98:101], v46 offset:24592
	ds_read_b128 v[102:105], v46 offset:28672
	ds_read_b128 v[106:109], v46 offset:28688
	ds_read_b128 v[110:113], v46 offset:32768
	ds_read_b128 v[114:117], v46 offset:32784
	v_add_u32_e32 v46, 32, v46
	s_waitcnt vmcnt(24)
	s_waitcnt lgkmcnt(0)
	v_pk_fma_f32 v[60:61], v[208:209], v[2:3], v[60:61] op_sel_hi:[1,0,1]
	v_pk_fma_f32 v[62:63], v[208:209], v[10:11], v[62:63] op_sel_hi:[1,0,1]
	v_pk_fma_f32 v[64:65], v[208:209], v[18:19], v[64:65] op_sel_hi:[1,0,1]
	v_pk_fma_f32 v[66:67], v[208:209], v[26:27], v[66:67] op_sel_hi:[1,0,1]
	v_pk_fma_f32 v[68:69], v[208:209], v[34:35], v[68:69] op_sel_hi:[1,0,1]
	v_pk_fma_f32 v[70:71], v[208:209], v[86:87], v[70:71] op_sel_hi:[1,0,1]
	v_pk_fma_f32 v[72:73], v[208:209], v[94:95], v[72:73] op_sel_hi:[1,0,1]
	v_pk_fma_f32 v[74:75], v[208:209], v[102:103], v[74:75] op_sel_hi:[1,0,1]
	v_pk_fma_f32 v[58:59], v[208:209], v[110:111], v[58:59] op_sel_hi:[1,0,1]
	v_pk_fma_f32 v[60:61], v[210:211], v[2:3], v[60:61] op_sel:[0,1,0]
	v_pk_fma_f32 v[62:63], v[210:211], v[10:11], v[62:63] op_sel:[0,1,0]
	v_pk_fma_f32 v[64:65], v[210:211], v[18:19], v[64:65] op_sel:[0,1,0]
	v_pk_fma_f32 v[66:67], v[210:211], v[26:27], v[66:67] op_sel:[0,1,0]
	v_pk_fma_f32 v[68:69], v[210:211], v[34:35], v[68:69] op_sel:[0,1,0]
	v_pk_fma_f32 v[70:71], v[210:211], v[86:87], v[70:71] op_sel:[0,1,0]
	v_pk_fma_f32 v[72:73], v[210:211], v[94:95], v[72:73] op_sel:[0,1,0]
	v_pk_fma_f32 v[74:75], v[210:211], v[102:103], v[74:75] op_sel:[0,1,0]
	v_pk_fma_f32 v[58:59], v[210:211], v[110:111], v[58:59] op_sel:[0,1,0]
	v_pk_fma_f32 v[60:61], v[212:213], v[4:5], v[60:61] op_sel_hi:[1,0,1]
	v_pk_fma_f32 v[62:63], v[212:213], v[12:13], v[62:63] op_sel_hi:[1,0,1]
	v_pk_fma_f32 v[64:65], v[212:213], v[20:21], v[64:65] op_sel_hi:[1,0,1]
	v_pk_fma_f32 v[66:67], v[212:213], v[28:29], v[66:67] op_sel_hi:[1,0,1]
	v_pk_fma_f32 v[68:69], v[212:213], v[36:37], v[68:69] op_sel_hi:[1,0,1]
	v_pk_fma_f32 v[70:71], v[212:213], v[88:89], v[70:71] op_sel_hi:[1,0,1]
	v_pk_fma_f32 v[72:73], v[212:213], v[96:97], v[72:73] op_sel_hi:[1,0,1]
	v_pk_fma_f32 v[74:75], v[212:213], v[104:105], v[74:75] op_sel_hi:[1,0,1]
	v_pk_fma_f32 v[58:59], v[212:213], v[112:113], v[58:59] op_sel_hi:[1,0,1]
	v_pk_fma_f32 v[60:61], v[214:215], v[4:5], v[60:61] op_sel:[0,1,0]
	v_pk_fma_f32 v[62:63], v[214:215], v[12:13], v[62:63] op_sel:[0,1,0]
	v_pk_fma_f32 v[64:65], v[214:215], v[20:21], v[64:65] op_sel:[0,1,0]
	v_pk_fma_f32 v[66:67], v[214:215], v[28:29], v[66:67] op_sel:[0,1,0]
	v_pk_fma_f32 v[68:69], v[214:215], v[36:37], v[68:69] op_sel:[0,1,0]
	v_pk_fma_f32 v[70:71], v[214:215], v[88:89], v[70:71] op_sel:[0,1,0]
	v_pk_fma_f32 v[72:73], v[214:215], v[96:97], v[72:73] op_sel:[0,1,0]
	v_pk_fma_f32 v[74:75], v[214:215], v[104:105], v[74:75] op_sel:[0,1,0]
	v_pk_fma_f32 v[58:59], v[214:215], v[112:113], v[58:59] op_sel:[0,1,0]
	v_pk_fma_f32 v[60:61], v[216:217], v[6:7], v[60:61] op_sel_hi:[1,0,1]
	v_pk_fma_f32 v[62:63], v[216:217], v[14:15], v[62:63] op_sel_hi:[1,0,1]
	v_pk_fma_f32 v[64:65], v[216:217], v[22:23], v[64:65] op_sel_hi:[1,0,1]
	v_pk_fma_f32 v[66:67], v[216:217], v[30:31], v[66:67] op_sel_hi:[1,0,1]
	v_pk_fma_f32 v[68:69], v[216:217], v[38:39], v[68:69] op_sel_hi:[1,0,1]
	v_pk_fma_f32 v[70:71], v[216:217], v[90:91], v[70:71] op_sel_hi:[1,0,1]
	v_pk_fma_f32 v[72:73], v[216:217], v[98:99], v[72:73] op_sel_hi:[1,0,1]
	v_pk_fma_f32 v[74:75], v[216:217], v[106:107], v[74:75] op_sel_hi:[1,0,1]
	v_pk_fma_f32 v[58:59], v[216:217], v[114:115], v[58:59] op_sel_hi:[1,0,1]
	v_pk_fma_f32 v[60:61], v[218:219], v[6:7], v[60:61] op_sel:[0,1,0]
	v_pk_fma_f32 v[62:63], v[218:219], v[14:15], v[62:63] op_sel:[0,1,0]
	v_pk_fma_f32 v[64:65], v[218:219], v[22:23], v[64:65] op_sel:[0,1,0]
	v_pk_fma_f32 v[66:67], v[218:219], v[30:31], v[66:67] op_sel:[0,1,0]
	v_pk_fma_f32 v[68:69], v[218:219], v[38:39], v[68:69] op_sel:[0,1,0]
	v_pk_fma_f32 v[70:71], v[218:219], v[90:91], v[70:71] op_sel:[0,1,0]
	v_pk_fma_f32 v[72:73], v[218:219], v[98:99], v[72:73] op_sel:[0,1,0]
	v_pk_fma_f32 v[74:75], v[218:219], v[106:107], v[74:75] op_sel:[0,1,0]
	v_pk_fma_f32 v[58:59], v[218:219], v[114:115], v[58:59] op_sel:[0,1,0]
	v_pk_fma_f32 v[60:61], v[220:221], v[8:9], v[60:61] op_sel_hi:[1,0,1]
	v_pk_fma_f32 v[62:63], v[220:221], v[16:17], v[62:63] op_sel_hi:[1,0,1]
	v_pk_fma_f32 v[64:65], v[220:221], v[24:25], v[64:65] op_sel_hi:[1,0,1]
	v_pk_fma_f32 v[66:67], v[220:221], v[32:33], v[66:67] op_sel_hi:[1,0,1]
	v_pk_fma_f32 v[68:69], v[220:221], v[40:41], v[68:69] op_sel_hi:[1,0,1]
	v_pk_fma_f32 v[70:71], v[220:221], v[92:93], v[70:71] op_sel_hi:[1,0,1]
	v_pk_fma_f32 v[72:73], v[220:221], v[100:101], v[72:73] op_sel_hi:[1,0,1]
	v_pk_fma_f32 v[74:75], v[220:221], v[108:109], v[74:75] op_sel_hi:[1,0,1]
	v_pk_fma_f32 v[58:59], v[220:221], v[116:117], v[58:59] op_sel_hi:[1,0,1]
	v_pk_fma_f32 v[60:61], v[222:223], v[8:9], v[60:61] op_sel:[0,1,0]
	v_pk_fma_f32 v[62:63], v[222:223], v[16:17], v[62:63] op_sel:[0,1,0]
	v_pk_fma_f32 v[64:65], v[222:223], v[24:25], v[64:65] op_sel:[0,1,0]
	v_pk_fma_f32 v[66:67], v[222:223], v[32:33], v[66:67] op_sel:[0,1,0]
	v_pk_fma_f32 v[68:69], v[222:223], v[40:41], v[68:69] op_sel:[0,1,0]
	v_pk_fma_f32 v[70:71], v[222:223], v[92:93], v[70:71] op_sel:[0,1,0]
	v_pk_fma_f32 v[72:73], v[222:223], v[100:101], v[72:73] op_sel:[0,1,0]
	v_pk_fma_f32 v[74:75], v[222:223], v[108:109], v[74:75] op_sel:[0,1,0]
	v_pk_fma_f32 v[58:59], v[222:223], v[116:117], v[58:59] op_sel:[0,1,0]
	s_add_i32 s53, s53, 1
	s_cmp_lt_u32 s53, 4
	s_cbranch_scc1 .Lmy_gk
	s_waitcnt vmcnt(0)
	s_mul_i32 s15, s45, 0x2400
	v_lshl_or_b32 v4, s44, 7, v80
	v_subrev_u32_e32 v4, s15, v4
	v_or_b32_e32 v2, s14, v80
	v_ashrrev_i32_e32 v5, 31, v4
	v_add_u32_e32 v2, s15, v2
	v_lshlrev_b64 v[4:5], 2, v[4:5]
	v_ashrrev_i32_e32 v3, 31, v2
	v_mad_i64_i32 v[4:5], s[14:15], s45, v85, v[4:5]
	v_lshl_add_u64 v[2:3], v[2:3], 2, s[10:11]
	v_lshl_add_u64 v[4:5], v[52:53], 0, v[4:5]
	s_mov_b64 s[14:15], 0
	v_mov_b32_e32 v6, v83
	v_mov_b32_e32 v7, v82
	ds_write2st64_b32 v79, v60, v61 offset0:144 offset1:145
	ds_write2st64_b32 v79, v62, v63 offset0:146 offset1:147
	ds_write2st64_b32 v79, v64, v65 offset0:148 offset1:149
	ds_write2st64_b32 v79, v66, v67 offset0:150 offset1:151
	ds_write2st64_b32 v79, v68, v69 offset0:152 offset1:153
	ds_write2st64_b32 v79, v70, v71 offset0:154 offset1:155
	ds_write2st64_b32 v79, v72, v73 offset0:156 offset1:157
	ds_write2st64_b32 v79, v74, v75 offset0:158 offset1:159
	ds_write2st64_b32 v79, v58, v59 offset0:160 offset1:161
	s_waitcnt lgkmcnt(0)
	s_barrier

.LBB0_20:
	v_lshlrev_b32_e32 v2, 5, v5
	v_and_b32_e32 v5, 0x60, v2
	v_ashrrev_i32_e32 v2, 31, v7
	v_mul_lo_u32 v10, s25, v7
	v_mul_lo_u32 v2, s24, v2
	v_mad_u64_u32 v[8:9], s[24:25], s24, v7, 0
	v_add3_u32 v9, v9, v2, v10
	v_lshlrev_b32_e32 v2, 1, v5
	v_lshlrev_b32_e32 v6, 2, v6
	v_mul_u32_u24_e32 v5, 0x204, v5
	v_lshl_add_u64 v[8:9], v[8:9], 1, s[22:23]
	s_ashr_i32 s29, s28, 31
	v_add3_u32 v5, 0, v6, v5
	v_lshl_add_u64 v[8:9], s[28:29], 1, v[8:9]
	v_add_u32_e32 v10, 0x400, v5
	ds_read2_b32 v[6:7], v5 offset1:129
	ds_read2_b32 v[10:11], v10 offset0:2 offset1:131
	v_add_u32_e32 v12, 0x800, v5
	v_add_u32_e32 v14, 0xc00, v5
	v_lshl_add_u64 v[16:17], v[8:9], 0, v[2:3]
	v_add_u32_e32 v2, 0x1000, v5
	ds_read2_b32 v[12:13], v12 offset0:4 offset1:133
	ds_read2_b32 v[14:15], v14 offset0:6 offset1:135
	s_waitcnt lgkmcnt(3)
	v_cvt_pk_bf16_f32 v6, v6, v7
	s_waitcnt lgkmcnt(2)
	v_cvt_pk_bf16_f32 v7, v10, v11
	s_waitcnt lgkmcnt(1)
	v_cvt_pk_bf16_f32 v8, v12, v13
	s_waitcnt lgkmcnt(0)
	v_cvt_pk_bf16_f32 v9, v14, v15
	ds_read2_b32 v[10:11], v2 offset0:8 offset1:137
	v_add_u32_e32 v2, 0x1400, v5
	ds_read2_b32 v[12:13], v2 offset0:10 offset1:139
	v_add_u32_e32 v2, 0x1800, v5
	ds_read2_b32 v[14:15], v2 offset0:12 offset1:141
	v_add_u32_e32 v2, 0x1c00, v5
	ds_read2_b32 v[18:19], v2 offset0:14 offset1:143
	v_add_u32_e32 v2, 0x2000, v5
	global_store_dwordx4 v[16:17], v[6:9], off
	s_waitcnt lgkmcnt(3)
	v_cvt_pk_bf16_f32 v6, v10, v11
	s_waitcnt lgkmcnt(2)
	v_cvt_pk_bf16_f32 v7, v12, v13
	s_waitcnt lgkmcnt(1)
	v_cvt_pk_bf16_f32 v8, v14, v15
	s_waitcnt lgkmcnt(0)
	v_cvt_pk_bf16_f32 v9, v18, v19
	ds_read2_b32 v[10:11], v2 offset0:16 offset1:145
	v_add_u32_e32 v2, 0x2400, v5
	ds_read2_b32 v[12:13], v2 offset0:18 offset1:147
	v_add_u32_e32 v2, 0x2800, v5
	ds_read2_b32 v[14:15], v2 offset0:20 offset1:149
	v_add_u32_e32 v2, 0x2c00, v5
	ds_read2_b32 v[18:19], v2 offset0:22 offset1:151
	v_add_u32_e32 v2, 0x3000, v5
	global_store_dwordx4 v[16:17], v[6:9], off offset:16
	s_waitcnt lgkmcnt(3)
	s_nop 0
	v_cvt_pk_bf16_f32 v6, v10, v11
	s_waitcnt lgkmcnt(2)
	v_cvt_pk_bf16_f32 v7, v12, v13
	s_waitcnt lgkmcnt(1)
	v_cvt_pk_bf16_f32 v8, v14, v15
	s_waitcnt lgkmcnt(0)
	v_cvt_pk_bf16_f32 v9, v18, v19
	ds_read2_b32 v[10:11], v2 offset0:24 offset1:153
	v_add_u32_e32 v2, 0x3400, v5
	ds_read2_b32 v[12:13], v2 offset0:26 offset1:155
	v_add_u32_e32 v2, 0x3800, v5
	ds_read2_b32 v[14:15], v2 offset0:28 offset1:157
	v_add_u32_e32 v2, 0x3c00, v5
	ds_read2_b32 v[18:19], v2 offset0:30 offset1:159
	global_store_dwordx4 v[16:17], v[6:9], off offset:32
	s_waitcnt lgkmcnt(3)
	s_nop 0
	v_cvt_pk_bf16_f32 v6, v10, v11
	s_waitcnt lgkmcnt(2)
	v_cvt_pk_bf16_f32 v7, v12, v13
	s_waitcnt lgkmcnt(1)
	v_cvt_pk_bf16_f32 v8, v14, v15
	s_waitcnt lgkmcnt(0)
	v_cvt_pk_bf16_f32 v9, v18, v19
	global_store_dwordx4 v[16:17], v[6:9], off offset:48
	s_barrier
	s_add_i32 s92, s92, s90
	s_cmp_lg_u32 s90, s42
	s_cbranch_scc1 .Lmy_cv_nomap
	s_cmp_lg_u32 s94, 0
	s_cbranch_scc1 .Lmy_cv_nomap
	s_cmpk_lt_i32 s92, 768
	s_cbranch_scc1 .Lmy_cv_nomap
	s_sub_i32 s91, s92, 768
	s_cmpk_gt_i32 s91, 111
	s_cselect_b32 s92, 0x7fff, s92
	s_movk_i32 s90, 112
